# attention A: QK K-fragment LDS reads 3-4 deep in flight (extra quad v204..v207) instead of 2
# speedup vs baseline: 1.0129x; 1.0129x over previous
; DI int crow(int i, int hh) { return (i & 3) + 8 * (i >> 2) + 4 * hh; }
; DI f32x16 mfma32(bf16x8 a, bf16x8 b, f32x16 c) { return __builtin_amdgcn_mfma_f32_32x32x16_bf16(a, b, c, 0, 0, 0); }
; template <int VD, bool DIFF>
; DI void attn_dense(const Params& p, const u16* qkv, int ld, u16* o, const float* lam4, const float* subln,
;                            float lam_init, const float* sinks, char* smem) {
;     ...
;             for (int kb = 0; kb < 2; ++kb) {
;               f32x16 S;
; #pragma unroll
;               for (int i = 0; i < 16; ++i) S[i] = 0.f;
; #pragma unroll
;               for (int s = 0; s < 4; ++s) {
;                 bf16x8 a = *(const bf16x8*)(sK + (32 * kb + l31) * 144 + (2 * s + hh) * 16);
;                 S = mfma32(a, qf[s], S);
;               }
;               if (far) {
; #pragma unroll
;                 for (int i = 0; i < 16; ++i) S[i] = __builtin_amdgcn_exp2f(S[i] + bfar);
;               } else {
; #pragma unroll
;                 for (int i = 0; i < 16; ++i) {
;                   const int kl = 32 * kb + crow(i, hh);
;                   S[i] = __builtin_amdgcn_exp2f(S[i] + bias_lookup(s_relb, s_btab, start + kl - qpos, bh));
;                 }
;               }
.LBB0_881:
	s_cmp_eq_u32 s52, 0
	s_cselect_b64 s[20:21], -1, 0
	s_cmp_le_i32 s52, s50
	s_cselect_b64 s[22:23], -1, 0
	s_or_b64 s[22:23], s[20:21], s[22:23]
	s_andn2_b64 vcc, exec, s[22:23]
	s_cbranch_vccnz .LBB0_891
	s_bitcmp1_b32 s52, 0
	s_cselect_b32 s5, 0x7400, 0
	v_or_b32_e32 v64, s5, v134
	v_add_u32_e32 v96, v64, v171
	ds_read_b128 v[64:67], v96
	ds_read_b128 v[68:71], v96 offset:32
	ds_read_b128 v[204:207], v96 offset:64
	s_sub_i32 s17, s2, 64
	s_and_b64 s[22:23], s[20:21], exec
	s_cselect_b32 s17, 0, s17
	s_waitcnt lgkmcnt(2)
	v_mfma_f32_32x32x16_bf16 v[80:95], v[64:67], v[104:107], 0
	ds_read_b128 v[64:67], v96 offset:96
	s_sub_i32 s22, s17, s6
	s_add_i32 s22, s22, 63
	s_cmpk_gt_i32 s22, 0xffa5
	s_cselect_b64 s[22:23], -1, 0
	v_add_u32_e32 v194, s17, v191
	s_mov_b64 s[26:27], -1
	s_waitcnt lgkmcnt(2)
	v_mfma_f32_32x32x16_bf16 v[80:95], v[68:71], v[108:111], v[80:95]
	s_and_b64 vcc, exec, s[22:23]
	s_waitcnt lgkmcnt(1)
	v_mfma_f32_32x32x16_bf16 v[80:95], v[204:207], v[112:115], v[80:95]
	s_waitcnt lgkmcnt(0)
	v_mfma_f32_32x32x16_bf16 v[80:95], v[64:67], v[116:119], v[80:95]
	v_add3_u32 v203, s5, v172, v170
	v_add_u32_e32 v203, v203, v146
	ds_read_b64_tr_b16 v[222:223], v203 offset:9216
	ds_read_b64_tr_b16 v[224:225], v203 offset:11776
	ds_read_b64_tr_b16 v[226:227], v203 offset:14336
	ds_read_b64_tr_b16 v[228:229], v203 offset:16896
	ds_read_b64_tr_b16 v[230:231], v203 offset:9280
	ds_read_b64_tr_b16 v[232:233], v203 offset:11840
	ds_read_b64_tr_b16 v[234:235], v203 offset:14400
	ds_read_b64_tr_b16 v[236:237], v203 offset:16960
	ds_read_b64_tr_b16 v[238:239], v203 offset:9344
	ds_read_b64_tr_b16 v[240:241], v203 offset:11904
	ds_read_b64_tr_b16 v[242:243], v203 offset:14464
	ds_read_b64_tr_b16 v[244:245], v203 offset:17024
	ds_read_b64_tr_b16 v[246:247], v203 offset:9408
	ds_read_b64_tr_b16 v[248:249], v203 offset:11968
	s_cbranch_vccz .LBB0_884
	v_add_u32_e32 v65, 1, v194
	v_add_u32_e32 v66, 2, v194
	v_add_u32_e32 v67, 3, v194
	v_add_u32_e32 v68, 8, v194
	v_add_u32_e32 v69, 9, v194
	v_add_u32_e32 v70, 10, v194
	v_add_u32_e32 v71, 11, v194
	v_med3_i32 v64, v194, s31, v217
	v_med3_i32 v65, v65, s31, v217
	v_med3_i32 v66, v66, s31, v217
	v_med3_i32 v67, v67, s31, v217
	v_med3_i32 v68, v68, s31, v217
	v_med3_i32 v69, v69, s31, v217
	v_med3_i32 v70, v70, s31, v217
	v_med3_i32 v71, v71, s31, v217
	v_add_u32_e32 v64, 0x1f080, v64
	v_add_u32_e32 v65, 0x1f080, v65
	v_add_u32_e32 v66, 0x1f080, v66
	v_add_u32_e32 v67, 0x1f080, v67
	v_add_u32_e32 v68, 0x1f080, v68
	v_add_u32_e32 v69, 0x1f080, v69
	v_add_u32_e32 v70, 0x1f080, v70
	v_add_u32_e32 v71, 0x1f080, v71
	ds_read_u8 v64, v64
	ds_read_u8 v65, v65
	ds_read_u8 v66, v66
	ds_read_u8 v67, v67
	ds_read_u8 v68, v68
	ds_read_u8 v69, v69
	ds_read_u8 v70, v70
	ds_read_u8 v71, v71
	v_add_u32_e32 v72, 16, v194
	v_add_u32_e32 v73, 17, v194
	v_add_u32_e32 v74, 18, v194
	v_add_u32_e32 v75, 19, v194
	v_add_u32_e32 v76, 24, v194
	v_add_u32_e32 v77, 25, v194
	v_add_u32_e32 v78, 26, v194
	v_add_u32_e32 v79, 27, v194
	v_med3_i32 v72, v72, s31, v217
	v_med3_i32 v73, v73, s31, v217
	v_med3_i32 v74, v74, s31, v217
	v_med3_i32 v75, v75, s31, v217
	v_med3_i32 v76, v76, s31, v217
	v_med3_i32 v77, v77, s31, v217
	v_med3_i32 v78, v78, s31, v217
	v_med3_i32 v79, v79, s31, v217
	s_waitcnt lgkmcnt(7)
	v_lshl_add_u32 v64, v64, 6, s51
	s_waitcnt lgkmcnt(6)
	v_lshl_add_u32 v65, v65, 6, s51
	s_waitcnt lgkmcnt(5)
	v_lshl_add_u32 v66, v66, 6, s51
	s_waitcnt lgkmcnt(4)
	v_lshl_add_u32 v67, v67, 6, s51
	s_waitcnt lgkmcnt(3)
	v_lshl_add_u32 v68, v68, 6, s51
	s_waitcnt lgkmcnt(2)
	v_lshl_add_u32 v69, v69, 6, s51
	s_waitcnt lgkmcnt(1)
	v_lshl_add_u32 v70, v70, 6, s51
	s_waitcnt lgkmcnt(0)
	v_lshl_add_u32 v71, v71, 6, s51
	v_add_u32_e32 v72, 0x1f080, v72
	v_add_u32_e32 v73, 0x1f080, v73
	v_add_u32_e32 v74, 0x1f080, v74
	v_add_u32_e32 v75, 0x1f080, v75
	v_add_u32_e32 v76, 0x1f080, v76
	v_add_u32_e32 v77, 0x1f080, v77
	v_add_u32_e32 v78, 0x1f080, v78
	v_add_u32_e32 v79, 0x1f080, v79
	ds_read_b32 v64, v64 offset:59392
	ds_read_b32 v65, v65 offset:59392
	ds_read_b32 v66, v66 offset:59392
	ds_read_b32 v67, v67 offset:59392
	ds_read_b32 v68, v68 offset:59392
	ds_read_b32 v69, v69 offset:59392
	ds_read_b32 v70, v70 offset:59392
	ds_read_b32 v71, v71 offset:59392
	ds_read_u8 v72, v72
	ds_read_u8 v73, v73
	ds_read_u8 v74, v74
	ds_read_u8 v75, v75
	ds_read_u8 v76, v76
	ds_read_u8 v77, v77
	ds_read_u8 v78, v78
	ds_read_u8 v79, v79
	s_waitcnt lgkmcnt(7)
	v_lshl_add_u32 v72, v72, 6, s51
	s_waitcnt lgkmcnt(6)
	v_lshl_add_u32 v73, v73, 6, s51
	s_waitcnt lgkmcnt(5)
	v_lshl_add_u32 v74, v74, 6, s51
	s_waitcnt lgkmcnt(4)
	v_lshl_add_u32 v75, v75, 6, s51
	s_waitcnt lgkmcnt(3)
	v_lshl_add_u32 v76, v76, 6, s51
	s_waitcnt lgkmcnt(2)
	v_lshl_add_u32 v77, v77, 6, s51
	s_waitcnt lgkmcnt(1)
	v_lshl_add_u32 v78, v78, 6, s51
	s_waitcnt lgkmcnt(0)
	v_lshl_add_u32 v79, v79, 6, s51
	ds_read_b32 v72, v72 offset:59392
	ds_read_b32 v73, v73 offset:59392
	ds_read_b32 v74, v74 offset:59392
	ds_read_b32 v75, v75 offset:59392
	ds_read_b32 v76, v76 offset:59392
	ds_read_b32 v77, v77 offset:59392
	ds_read_b32 v78, v78 offset:59392
	ds_read_b32 v79, v79 offset:59392
	v_add_f32_e32 v64, v80, v64
	v_add_f32_e32 v65, v81, v65
	v_add_f32_e32 v66, v82, v66
	v_add_f32_e32 v67, v83, v67
	v_add_f32_e32 v68, v84, v68
	v_add_f32_e32 v69, v85, v69
	v_add_f32_e32 v70, v86, v70
	v_add_f32_e32 v71, v87, v71
	s_waitcnt lgkmcnt(7)
	v_add_f32_e32 v72, v88, v72
	s_waitcnt lgkmcnt(6)
	v_add_f32_e32 v73, v89, v73
	s_waitcnt lgkmcnt(5)
	v_add_f32_e32 v74, v90, v74
	s_waitcnt lgkmcnt(4)
	v_add_f32_e32 v75, v91, v75
	s_waitcnt lgkmcnt(3)
	v_add_f32_e32 v76, v92, v76
	s_waitcnt lgkmcnt(2)
	v_add_f32_e32 v77, v93, v77
	s_waitcnt lgkmcnt(1)
	v_add_f32_e32 v78, v94, v78
	v_exp_f32_e32 v64, v64
	v_exp_f32_e32 v65, v65
	v_exp_f32_e32 v66, v66
	v_exp_f32_e32 v67, v67
	v_exp_f32_e32 v68, v68
	v_exp_f32_e32 v69, v69
	v_exp_f32_e32 v70, v70
	v_exp_f32_e32 v71, v71
	v_exp_f32_e32 v72, v72
	v_exp_f32_e32 v73, v73
	v_exp_f32_e32 v74, v74
	v_exp_f32_e32 v75, v75
	v_exp_f32_e32 v76, v76
	v_exp_f32_e32 v77, v77
	v_exp_f32_e32 v78, v78
	s_waitcnt lgkmcnt(0)
	v_add_f32_e32 v79, v95, v79
	s_mov_b64 s[26:27], 0

; DI int crow(int i, int hh) { return (i & 3) + 8 * (i >> 2) + 4 * hh; }
; DI f32x16 mfma32(bf16x8 a, bf16x8 b, f32x16 c) { return __builtin_amdgcn_mfma_f32_32x32x16_bf16(a, b, c, 0, 0, 0); }
; DI bf16x8 cat8(s16x4 lo, s16x4 hi) { return __builtin_shufflevector(lo, hi, 0, 1, 2, 3, 4, 5, 6, 7); }
; template <int VD, bool DIFF>
; DI void attn_dense(const Params& p, const u16* qkv, int ld, u16* o, const float* lam4, const float* subln,
;                            float lam_init, const float* sinks, char* smem) {
;     ...
;             for (int kb = 0; kb < 2; ++kb) {
;               f32x16 S;
; #pragma unroll
;               for (int i = 0; i < 16; ++i) S[i] = 0.f;
; #pragma unroll
;               for (int s = 0; s < 4; ++s) {
;                 bf16x8 a = *(const bf16x8*)(sK + (32 * kb + l31) * 144 + (2 * s + hh) * 16);
;                 S = mfma32(a, qf[s], S);
;               }
;     ...
;               if (valid < 64) {
; #pragma unroll
;                 for (int i = 0; i < 16; ++i) {
;                   const int kl = 32 * kb + crow(i, hh);
;                   S[i] = kl < valid ? S[i] : 0.f;
;                 }
;               }
; #pragma unroll
;               for (int i = 0; i < 16; ++i) l += S[i];
;               bf16x8 pf[2];
; #pragma unroll
;               for (int s2 = 0; s2 < 2; ++s2)
;                 pf[s2] = mk8(pack2(S[8 * s2], S[8 * s2 + 1]), pack2(S[8 * s2 + 2], S[8 * s2 + 3]),
;                              pack2(S[8 * s2 + 4], S[8 * s2 + 5]), pack2(S[8 * s2 + 6], S[8 * s2 + 7]));
; #pragma unroll
;               for (int d_ = 0; d_ < NDB; ++d_) {
; #pragma unroll
;                 for (int s2 = 0; s2 < 2; ++s2) {
;                   const int k0 = 32 * kb + 16 * s2 + 4 * hh + q4;
;                   s16x4 lo = tr_read(sV + k0 * VS + (32 * d_ + 16 * blk) * 2 + 8 * p4);
;                   s16x4 hi = tr_read(sV + (k0 + 8) * VS + (32 * d_ + 16 * blk) * 2 + 8 * p4);
;                   O[d_] = mfma32(cat8(lo, hi), pf[s2], O[d_]);
;                 }
;               }
.LBB0_886:
	s_nop 8
	v_add3_u32 v80, s5, v172, v170
	v_add_u32_e32 v157, v80, v146
	ds_read_b64_tr_b16 v[80:81], v157 offset:14528
	ds_read_b64_tr_b16 v[82:83], v157 offset:17088
	v_cndmask_b32_e64 v199, v75, 0, s[20:21]
	v_cndmask_b32_e64 v200, v74, 0, s[20:21]
	v_cndmask_b32_e64 v201, v73, 0, s[20:21]
	v_cndmask_b32_e64 v202, v72, 0, s[20:21]
	v_cvt_pk_bf16_f32 v72, v64, v65
	v_cvt_pk_bf16_f32 v73, v66, v67
	v_cvt_pk_bf16_f32 v74, v68, v69
	v_cvt_pk_bf16_f32 v75, v70, v71
	v_exp_f32_e32 v79, v79
	v_cndmask_b32_e64 v196, v78, 0, s[20:21]
	s_waitcnt lgkmcnt(2)
	v_mfma_f32_32x32x16_bf16 v[48:63], v[222:225], v[72:75], v[48:63]
	v_cndmask_b32_e64 v195, v79, 0, s[20:21]
	v_cndmask_b32_e64 v197, v77, 0, s[20:21]
	v_cndmask_b32_e64 v198, v76, 0, s[20:21]
	v_cvt_pk_bf16_f32 v76, v202, v201
	v_cvt_pk_bf16_f32 v77, v200, v199
	v_cvt_pk_bf16_f32 v78, v198, v197
	v_cvt_pk_bf16_f32 v79, v196, v195
	s_nop 0
	s_nop 0
	v_mfma_f32_32x32x16_bf16 v[48:63], v[226:229], v[76:79], v[48:63]
	v_mfma_f32_32x32x16_bf16 v[32:47], v[230:233], v[72:75], v[32:47]
	v_mfma_f32_32x32x16_bf16 v[32:47], v[234:237], v[76:79], v[32:47]
	v_mfma_f32_32x32x16_bf16 v[16:31], v[238:241], v[72:75], v[16:31]
	v_mfma_f32_32x32x16_bf16 v[16:31], v[242:245], v[76:79], v[16:31]
	v_mfma_f32_32x32x16_bf16 v[0:15], v[246:249], v[72:75], v[0:15]
	s_waitcnt lgkmcnt(0)
	v_mfma_f32_32x32x16_bf16 v[0:15], v[80:83], v[76:79], v[0:15]
	ds_read_b128 v[72:75], v96 offset:4608
	ds_read_b128 v[88:91], v96 offset:4640
	ds_read_b128 v[204:207], v96 offset:4672
	ds_read_b128 v[92:95], v96 offset:4704
	s_andn2_b64 vcc, exec, s[22:23]
	s_mov_b64 s[22:23], -1
	s_waitcnt lgkmcnt(3)
	v_mfma_f32_32x32x16_bf16 v[72:87], v[72:75], v[104:107], 0
	s_waitcnt lgkmcnt(2)
	v_mfma_f32_32x32x16_bf16 v[72:87], v[88:91], v[108:111], v[72:87]
	s_waitcnt lgkmcnt(1)
	v_mfma_f32_32x32x16_bf16 v[72:87], v[204:207], v[112:115], v[72:87]
	s_waitcnt lgkmcnt(0)
	v_mfma_f32_32x32x16_bf16 v[72:87], v[92:95], v[116:119], v[72:87]
	ds_read_b64_tr_b16 v[222:223], v157 offset:19456
	ds_read_b64_tr_b16 v[224:225], v157 offset:22016
	ds_read_b64_tr_b16 v[226:227], v157 offset:24576
	ds_read_b64_tr_b16 v[228:229], v157 offset:27136
	ds_read_b64_tr_b16 v[230:231], v157 offset:19520
	ds_read_b64_tr_b16 v[232:233], v157 offset:22080
	ds_read_b64_tr_b16 v[234:235], v157 offset:24640
	ds_read_b64_tr_b16 v[236:237], v157 offset:27200
	ds_read_b64_tr_b16 v[238:239], v157 offset:19584
	ds_read_b64_tr_b16 v[240:241], v157 offset:22144
	ds_read_b64_tr_b16 v[242:243], v157 offset:24704
	ds_read_b64_tr_b16 v[244:245], v157 offset:27264
	ds_read_b64_tr_b16 v[246:247], v157 offset:19648
	ds_read_b64_tr_b16 v[248:249], v157 offset:22208
	s_cbranch_vccnz .LBB0_888
; DI int crow(int i, int hh) { return (i & 3) + 8 * (i >> 2) + 4 * hh; }
; template <int VD, bool DIFF>
; DI void attn_dense(const Params& p, const u16* qkv, int ld, u16* o, const float* lam4, const float* subln,
;                            float lam_init, const float* sinks, char* smem) {
;     ...
;               } else {
; #pragma unroll
;                 for (int i = 0; i < 16; ++i) {
;                   const int kl = 32 * kb + crow(i, hh);
;                   S[i] = __builtin_amdgcn_exp2f(S[i] + bias_lookup(s_relb, s_btab, start + kl - qpos, bh));
;                 }
	v_add_u32_e32 v88, 32, v194
	v_add_u32_e32 v89, 33, v194
	v_add_u32_e32 v90, 34, v194
	v_add_u32_e32 v91, 35, v194
	v_add_u32_e32 v92, 40, v194
	v_add_u32_e32 v93, 41, v194
	v_add_u32_e32 v94, 42, v194
	v_add_u32_e32 v95, 43, v194
	v_med3_i32 v88, v88, s31, v217
	v_med3_i32 v89, v89, s31, v217
	v_med3_i32 v90, v90, s31, v217
	v_med3_i32 v91, v91, s31, v217
	v_med3_i32 v92, v92, s31, v217
	v_med3_i32 v93, v93, s31, v217
	v_med3_i32 v94, v94, s31, v217
	v_med3_i32 v95, v95, s31, v217
	v_add_u32_e32 v88, 0x1f080, v88
	v_add_u32_e32 v89, 0x1f080, v89
	v_add_u32_e32 v90, 0x1f080, v90
	v_add_u32_e32 v91, 0x1f080, v91
	v_add_u32_e32 v92, 0x1f080, v92
	v_add_u32_e32 v93, 0x1f080, v93
	v_add_u32_e32 v94, 0x1f080, v94
	v_add_u32_e32 v95, 0x1f080, v95
	ds_read_u8 v88, v88
	ds_read_u8 v89, v89
	ds_read_u8 v90, v90
	ds_read_u8 v91, v91
	ds_read_u8 v92, v92
	ds_read_u8 v93, v93
	ds_read_u8 v94, v94
	ds_read_u8 v95, v95
	v_add_u32_e32 v96, 48, v194
	v_add_u32_e32 v97, 49, v194
	v_add_u32_e32 v98, 50, v194
	v_add_u32_e32 v99, 51, v194
	v_add_u32_e32 v100, 56, v194
	v_add_u32_e32 v101, 57, v194
	v_add_u32_e32 v102, 58, v194
	v_add_u32_e32 v103, 59, v194
	v_med3_i32 v96, v96, s31, v217
	v_med3_i32 v97, v97, s31, v217
	v_med3_i32 v98, v98, s31, v217
	v_med3_i32 v99, v99, s31, v217
	v_med3_i32 v100, v100, s31, v217
	v_med3_i32 v101, v101, s31, v217
	v_med3_i32 v102, v102, s31, v217
	v_med3_i32 v103, v103, s31, v217
	s_waitcnt lgkmcnt(7)
	v_lshl_add_u32 v88, v88, 6, s51
	s_waitcnt lgkmcnt(6)
	v_lshl_add_u32 v89, v89, 6, s51
	s_waitcnt lgkmcnt(5)
	v_lshl_add_u32 v90, v90, 6, s51
	s_waitcnt lgkmcnt(4)
	v_lshl_add_u32 v91, v91, 6, s51
	s_waitcnt lgkmcnt(3)
	v_lshl_add_u32 v92, v92, 6, s51
	s_waitcnt lgkmcnt(2)
	v_lshl_add_u32 v93, v93, 6, s51
	s_waitcnt lgkmcnt(1)
	v_lshl_add_u32 v94, v94, 6, s51
	s_waitcnt lgkmcnt(0)
	v_lshl_add_u32 v95, v95, 6, s51
	v_add_u32_e32 v96, 0x1f080, v96
	v_add_u32_e32 v97, 0x1f080, v97
	v_add_u32_e32 v98, 0x1f080, v98
	v_add_u32_e32 v99, 0x1f080, v99
	v_add_u32_e32 v100, 0x1f080, v100
	v_add_u32_e32 v101, 0x1f080, v101
	v_add_u32_e32 v102, 0x1f080, v102
	v_add_u32_e32 v103, 0x1f080, v103
	ds_read_b32 v88, v88 offset:59392
	ds_read_b32 v89, v89 offset:59392
	ds_read_b32 v90, v90 offset:59392
	ds_read_b32 v91, v91 offset:59392
	ds_read_b32 v92, v92 offset:59392
	ds_read_b32 v93, v93 offset:59392
	ds_read_b32 v94, v94 offset:59392
	ds_read_b32 v95, v95 offset:59392
	ds_read_u8 v96, v96
	ds_read_u8 v97, v97
	ds_read_u8 v98, v98
	ds_read_u8 v99, v99
	ds_read_u8 v100, v100
	ds_read_u8 v101, v101
	ds_read_u8 v102, v102
	ds_read_u8 v103, v103
	s_waitcnt lgkmcnt(7)
	v_lshl_add_u32 v96, v96, 6, s51
	s_waitcnt lgkmcnt(6)
	v_lshl_add_u32 v97, v97, 6, s51
	s_waitcnt lgkmcnt(5)
	v_lshl_add_u32 v98, v98, 6, s51
	s_waitcnt lgkmcnt(4)
	v_lshl_add_u32 v99, v99, 6, s51
	s_waitcnt lgkmcnt(3)
	v_lshl_add_u32 v100, v100, 6, s51
	s_waitcnt lgkmcnt(2)
	v_lshl_add_u32 v101, v101, 6, s51
	s_waitcnt lgkmcnt(1)
	v_lshl_add_u32 v102, v102, 6, s51
	s_waitcnt lgkmcnt(0)
	v_lshl_add_u32 v103, v103, 6, s51
	ds_read_b32 v96, v96 offset:59392
	ds_read_b32 v97, v97 offset:59392
	ds_read_b32 v98, v98 offset:59392
	ds_read_b32 v99, v99 offset:59392
	ds_read_b32 v100, v100 offset:59392
	ds_read_b32 v101, v101 offset:59392
	ds_read_b32 v102, v102 offset:59392
	ds_read_b32 v103, v103 offset:59392
	v_add_f32_e32 v88, v72, v88
	v_add_f32_e32 v89, v73, v89
	v_add_f32_e32 v90, v74, v90
	v_add_f32_e32 v91, v75, v91
	v_add_f32_e32 v92, v76, v92
	v_add_f32_e32 v93, v77, v93
	v_add_f32_e32 v94, v78, v94
	v_add_f32_e32 v95, v79, v95
	s_waitcnt lgkmcnt(7)
	v_add_f32_e32 v96, v80, v96
	s_waitcnt lgkmcnt(6)
	v_add_f32_e32 v97, v81, v97
	s_waitcnt lgkmcnt(5)
	v_add_f32_e32 v98, v82, v98
	s_waitcnt lgkmcnt(4)
	v_add_f32_e32 v99, v83, v99
	s_waitcnt lgkmcnt(3)
	v_add_f32_e32 v100, v84, v100
	s_waitcnt lgkmcnt(2)
	v_add_f32_e32 v101, v85, v101
	s_waitcnt lgkmcnt(1)
	v_add_f32_e32 v102, v86, v102
	v_exp_f32_e32 v88, v88
	v_exp_f32_e32 v89, v89
	v_exp_f32_e32 v90, v90
	v_exp_f32_e32 v91, v91
	v_exp_f32_e32 v92, v92
	v_exp_f32_e32 v93, v93
	v_exp_f32_e32 v94, v94
	v_exp_f32_e32 v95, v95
	v_exp_f32_e32 v96, v96
	v_exp_f32_e32 v97, v97
	v_exp_f32_e32 v98, v98
	v_exp_f32_e32 v99, v99
	v_exp_f32_e32 v100, v100
	v_exp_f32_e32 v101, v101
	v_exp_f32_e32 v102, v102
	s_waitcnt lgkmcnt(0)
	v_add_f32_e32 v103, v87, v103
	s_mov_b64 s[22:23], 0
